# stacked wait-at-first-consumer edits: row-scale tables of P4/P9 and P6 overlapped with the GEMM prologue DMA, q-fragment wait below the bias set-up
# baseline (speedup 1.0000x reference)
.LBB0_1149:
	s_mov_b64 s[0:1], -1
	v_writelane_b32 v255, s0, 56
	s_andn2_b64 vcc, exec, s[40:41]
	s_nop 0
	v_writelane_b32 v255, s1, 57
	s_mov_b64 s[0:1], -1
	s_cbranch_vccnz .LBB0_398
	v_readlane_b32 s0, v255, 0
	v_readlane_b32 s1, v255, 1
	s_andn2_b64 vcc, exec, s[0:1]
	s_cbranch_vccnz .LBB0_1305
	v_readlane_b32 s0, v253, 6
	v_readlane_b32 s1, v253, 7
	s_and_b64 vcc, exec, s[0:1]
	v_readlane_b32 s0, v254, 62
	v_readlane_b32 s1, v254, 63
	s_mov_b32 s22, 0
	s_nop 0
	v_cndmask_b32_e64 v0, 0, 1, s[0:1]
	v_cmp_ne_u32_e64 s[0:1], 1, v0
	s_cbranch_vccnz .LBB0_1157
	s_and_b64 vcc, exec, s[0:1]
	s_cbranch_vccnz .LBB0_1156
	v_mov_b32_e32 v0, v204
	s_movk_i32 s12, 0x100
	s_nop 0
	v_cmp_gt_i32_e32 vcc, s12, v0
	s_and_saveexec_b64 s[36:37], vcc
	s_cbranch_execz .LBB0_1155
	v_readlane_b32 s12, v255, 13
	s_nop 1
	v_add_u32_e32 v2, s12, v0
	s_waitcnt lgkmcnt(0)
	v_ashrrev_i32_e32 v3, 31, v2
	v_lshl_add_u64 v[2:3], v[2:3], 3, s[70:71]
	global_load_dwordx2 v[60:61], v[2:3], off
	v_lshl_add_u32 v0, v0, 2, 0
	v_add_u32_e32 v59, 0x20100, v0

.LBB0_1156:
.LBB0_1157:
	s_waitcnt lgkmcnt(0)
	v_mov_b32_e32 v3, v204
	s_and_b64 vcc, exec, s[0:1]
	v_readfirstlane_b32 s0, v3
	s_cbranch_vccnz .LBB0_1273
	v_lshlrev_b32_e32 v5, 4, v3
	v_add_u32_e32 v2, 0x2000, v5
	v_ashrrev_i32_e32 v0, 31, v2
	v_lshrrev_b32_e32 v0, 22, v0
	v_add_u32_e32 v0, v2, v0
	v_ashrrev_i32_e32 v0, 10, v0
	v_mul_i32_i24_e32 v4, 0x400, v0
	v_sub_u32_e32 v2, v2, v4
	v_lshrrev_b32_e32 v4, 4, v2
	v_bitop3_b32 v4, v4, v2, 32 bitop3:0x6c
	v_ashrrev_i32_e32 v2, 31, v4
	v_lshrrev_b32_e32 v2, 26, v2
	v_add_u32_e32 v6, v4, v2
	v_lshlrev_b32_e32 v7, 3, v0
	v_ashrrev_i32_e32 v2, 6, v6
	v_and_b32_e32 v7, -16, v7
	v_add_u32_e32 v7, v2, v7
	v_and_b32_e32 v8, 3, v2
	s_mov_b32 s12, 0x1fffe0
	v_lshrrev_b32_e32 v9, 2, v7
	v_lshlrev_b32_e32 v10, 1, v7
	v_and_b32_e32 v6, 0xc0, v6
	v_and_or_b32 v8, v7, s12, v8
	v_and_b32_e32 v9, 4, v9
	v_and_b32_e32 v10, 24, v10
	v_sub_u32_e32 v4, v4, v6
	v_or3_b32 v8, v8, v9, v10
	v_lshlrev_b32_e32 v9, 5, v0
	v_ashrrev_i16_sdwa v4, v224, sext(v4) dst_sel:DWORD dst_unused:UNUSED_PAD src0_sel:DWORD src1_sel:BYTE_0
	v_and_b32_e32 v9, 32, v9
	v_bfe_i32 v4, v4, 0, 16
	v_add_lshl_u32 v6, v9, v4, 1
	v_lshl_add_u32 v130, v8, 11, v6
	v_lshl_add_u32 v132, v7, 11, v6
	v_bfe_i32 v6, v3, 27, 1
	v_lshrrev_b32_e32 v6, 22, v6
	v_add_u32_e32 v6, v5, v6
	v_and_b32_e32 v6, 0xfffffc00, v6
	v_sub_u32_e32 v5, v5, v6
	v_lshrrev_b32_e32 v6, 4, v5
	v_bitop3_b32 v7, v6, v5, 32 bitop3:0x6c
	v_ashrrev_i32_e32 v6, 31, v3
	v_lshrrev_b32_e32 v6, 26, v6
	v_ashrrev_i32_e32 v5, 31, v5
	v_add_u32_e32 v6, v3, v6
	v_lshrrev_b32_e32 v5, 26, v5
	v_ashrrev_i32_e32 v6, 6, v6
	v_add_u32_e32 v5, v7, v5
	v_lshlrev_b32_e32 v8, 3, v6
	v_ashrrev_i32_e32 v5, 6, v5
	v_and_b32_e32 v8, -16, v8
	v_add_u32_e32 v8, v5, v8
	v_and_b32_e32 v9, 3, v5
	v_lshrrev_b32_e32 v10, 2, v8
	v_lshlrev_b32_e32 v11, 1, v8
	v_and_or_b32 v9, v8, s12, v9
	v_and_b32_e32 v10, 4, v10
	v_and_b32_e32 v11, 24, v11
	v_or3_b32 v9, v9, v10, v11
	v_mul_i32_i24_e32 v11, 64, v5
	v_sub_u32_e32 v7, v7, v11
	s_ashr_i32 s1, s0, 6
	v_lshlrev_b32_e32 v10, 5, v6
	v_ashrrev_i16_sdwa v7, v224, sext(v7) dst_sel:DWORD dst_unused:UNUSED_PAD src0_sel:DWORD src1_sel:BYTE_0
	s_lshl_b32 s19, s1, 10
	v_and_b32_e32 v10, 32, v10
	v_bfe_i32 v7, v7, 0, 16
	v_add_lshl_u32 v10, v10, v7, 1
	s_add_i32 s20, s19, 0
	v_readlane_b32 s12, v255, 41
	v_lshl_add_u32 v134, v9, 11, v10
	s_add_i32 m0, s20, 0x10000
	v_readlane_b32 s13, v255, 42
	v_lshl_add_u32 v136, v8, 11, v10
	s_add_i32 s21, s20, 0x2000
	s_add_i32 s72, s20, 0x4000
	s_add_i32 s80, s20, 0x6000
	s_ashr_i32 s23, s0, 8
	global_load_lds_dwordx4 v134, s[12:13]
	s_add_i32 m0, s20, 0x12000
	s_nop 0
	global_load_lds_dwordx4 v130, s[12:13]
	v_readlane_b32 s12, v255, 35
	s_add_i32 m0, s20, 0x14000
	v_readlane_b32 s13, v255, 36
	s_nop 4
	global_load_lds_dwordx4 v134, s[12:13]
	s_add_i32 m0, s20, 0x16000
	s_cmp_eq_u32 s23, 1
	global_load_lds_dwordx4 v130, s[12:13]
	v_readlane_b32 s12, v255, 37
	s_mov_b32 m0, s20
	v_readlane_b32 s13, v255, 38
	s_cselect_b64 s[36:37], -1, 0
	s_cmp_lg_u32 s23, 1
	s_nop 2
	global_load_lds_dwordx4 v136, s[12:13]
	s_mov_b32 m0, s21
	s_nop 0
	global_load_lds_dwordx4 v132, s[12:13]
	v_readlane_b32 s12, v255, 39
	s_mov_b32 m0, s72
	v_readlane_b32 s13, v255, 40
	s_nop 4
	global_load_lds_dwordx4 v136, s[12:13]
	s_mov_b32 m0, s80
	s_nop 0
	global_load_lds_dwordx4 v132, s[12:13]
	s_cbranch_scc1 .LBB0_1160
	s_barrier
.LBB0_1160:
	s_cmp_eq_u32 s22, 0
	s_cbranch_scc1 .Lmy_rst6_done
	v_cmp_gt_i32_e32 vcc, 0x100, v204
	s_and_saveexec_b64 s[98:99], vcc
	s_cbranch_execz .Lmy_rst6_skip
	s_waitcnt vmcnt(8)
	v_ffbh_u32_e32 v58, v61
	v_min_u32_e32 v58, 32, v58
	v_lshlrev_b64 v[60:61], v58, v[60:61]
	v_min_u32_e32 v60, 1, v60
	v_or_b32_e32 v60, v61, v60
	v_cvt_f32_u32_e32 v60, v60
	v_sub_u32_e32 v61, 32, v58
	v_ldexp_f32 v60, v60, v61
	v_fmamk_f32 v60, v60, 0x30800000, v207
	v_mul_f32_e32 v61, 0x4b800000, v60
	v_cmp_gt_f32_e32 vcc, s16, v60
	s_nop 1
	v_cndmask_b32_e32 v60, v60, v61, vcc
	v_rsq_f32_e32 v60, v60
	s_nop 0
	v_mul_f32_e32 v61, 0x45800000, v60
	v_cndmask_b32_e32 v60, v60, v61, vcc
	ds_write_b32 v59, v60
